# attention unit epilogues: row-per-lane bf16 output stores widened with v_permlane32_swap pairs (8x dwordx2 -> 4x dwordx4 per lane), on the v68 stack
# speedup vs baseline: 1.0092x; 1.0092x over previous
; #define GAS __attribute__((address_space(1)))
; __device__ __forceinline__ void store_frag_bf16(bf16_t* base, const f32x16& a, float sc, int hi) {
; #pragma unroll
;   for (int g = 0; g < 4; ++g) {
;     u32x2 w; w.x = pk_bf16(a[4 * g] * sc, a[4 * g + 1] * sc); w.y = pk_bf16(a[4 * g + 2] * sc, a[4 * g + 3] * sc);
;     *(GAS u32x2*)(base + 8 * g + 4 * hi) = w;
;   }
; }
; template <int MODE>
; __device__ __forceinline__ void attn_unit(const Params& P, int b, int h, int qb, unsigned char* smem) {
;     ...
;   const float lt = l_run + __shfl_xor(l_run, 32);
;   const float inv = 1.0f / lt;
; #pragma unroll
;   for (int db = 0; db < 2; ++db) store_frag_bf16(O + (size_t)qi * 1024 + 32 * db, oacc[db], inv, hi);
; __device__ __forceinline__ void phase_attn_even(const Params& P, unsigned char* smem) {
;     ...
;     const int u = j * G + ((j & 1) ? (G - 1 - bid) : bid);
;     if (u >= 1024) break;
.LBB0_839:
	s_or_b64 exec, exec, s[6:7]
	v_cmp_lt_i32_e32 vcc, v5, v7
	s_lshl_b32 s10, s25, 11
	s_nop 0
	v_cndmask_b32_e32 v2, v6, v5, vcc
	v_lshlrev_b32_e32 v2, 2, v2
	ds_bpermute_b32 v4, v2, v0
	v_lshl_add_u64 v[2:3], v[112:113], 0, s[10:11]
	s_lshl_b32 s10, s24, 1
	v_lshl_add_u64 v[2:3], v[2:3], 0, s[10:11]
	s_barrier
	s_waitcnt lgkmcnt(0)
	v_add_f32_e32 v0, v0, v4
	v_div_scale_f32 v4, s[6:7], v0, v0, 1.0
	v_rcp_f32_e32 v5, v4
	s_add_i32 s7, s23, 1
	s_bitcmp0_b32 s23, 0
	v_fma_f32 v6, -v4, v5, 1.0
	v_fmac_f32_e32 v5, v6, v5
	v_div_scale_f32 v6, vcc, 1.0, v0, 1.0
	v_mul_f32_e32 v7, v6, v5
	v_fma_f32 v8, -v4, v7, v6
	v_fmac_f32_e32 v7, v8, v5
	v_fma_f32 v4, -v4, v7, v6
	v_div_fmas_f32 v4, v4, v5, v7
	v_div_fixup_f32 v4, v4, v0, 1.0
	v_lshlrev_b64 v[6:7], 11, v[140:141]
	v_lshl_add_u64 v[2:3], v[2:3], 0, v[6:7]
	v_lshlrev_b32_e32 v0, 1, v144
	v_lshl_add_u64 v[2:3], v[2:3], 0, v[0:1]
	v_mbcnt_lo_u32_b32 v224, -1, 0
	v_mbcnt_hi_u32_b32 v224, -1, v224
	v_and_b32_e32 v224, 32, v224
	v_lshrrev_b32_e32 v224, 2, v224
	v_mov_b32_e32 v225, 0
	v_lshl_add_u64 v[2:3], v[2:3], 0, v[224:225]
	v_pk_mul_f32 v[6:7], v[96:97], v[4:5] op_sel_hi:[1,0]
	v_pk_mul_f32 v[8:9], v[98:99], v[4:5] op_sel_hi:[1,0]
	v_cvt_pk_bf16_f32 v216, v6, v7
	v_cvt_pk_bf16_f32 v217, v8, v9
	v_pk_mul_f32 v[6:7], v[100:101], v[4:5] op_sel_hi:[1,0]
	v_pk_mul_f32 v[8:9], v[102:103], v[4:5] op_sel_hi:[1,0]
	v_cvt_pk_bf16_f32 v218, v6, v7
	v_cvt_pk_bf16_f32 v219, v8, v9
	s_nop 1
	v_permlane32_swap_b32_e32 v216, v218
	v_permlane32_swap_b32_e32 v217, v219
	global_store_dwordx4 v[2:3], v[216:219], off offset:1024
	v_pk_mul_f32 v[6:7], v[104:105], v[4:5] op_sel_hi:[1,0]
	v_pk_mul_f32 v[8:9], v[106:107], v[4:5] op_sel_hi:[1,0]
	v_cvt_pk_bf16_f32 v220, v6, v7
	v_cvt_pk_bf16_f32 v221, v8, v9
	v_pk_mul_f32 v[6:7], v[108:109], v[4:5] op_sel_hi:[1,0]
	v_pk_mul_f32 v[8:9], v[110:111], v[4:5] op_sel_hi:[1,0]
	v_cvt_pk_bf16_f32 v222, v6, v7
	v_cvt_pk_bf16_f32 v223, v8, v9
	s_nop 1
	v_permlane32_swap_b32_e32 v220, v222
	v_permlane32_swap_b32_e32 v221, v223
	global_store_dwordx4 v[2:3], v[220:223], off offset:1056
	v_pk_mul_f32 v[6:7], v[80:81], v[4:5] op_sel_hi:[1,0]
	v_pk_mul_f32 v[8:9], v[82:83], v[4:5] op_sel_hi:[1,0]
	v_cvt_pk_bf16_f32 v216, v6, v7
	v_cvt_pk_bf16_f32 v217, v8, v9
	v_pk_mul_f32 v[6:7], v[84:85], v[4:5] op_sel_hi:[1,0]
	v_pk_mul_f32 v[8:9], v[86:87], v[4:5] op_sel_hi:[1,0]
	v_cvt_pk_bf16_f32 v218, v6, v7
	v_cvt_pk_bf16_f32 v219, v8, v9
	s_nop 1
	v_permlane32_swap_b32_e32 v216, v218
	v_permlane32_swap_b32_e32 v217, v219
	global_store_dwordx4 v[2:3], v[216:219], off offset:1088
	s_mul_i32 s6, s7, s38
	s_cselect_b32 s10, s53, s2
	v_pk_mul_f32 v[6:7], v[88:89], v[4:5] op_sel_hi:[1,0]
	v_pk_mul_f32 v[8:9], v[90:91], v[4:5] op_sel_hi:[1,0]
	v_cvt_pk_bf16_f32 v220, v6, v7
	v_cvt_pk_bf16_f32 v221, v8, v9
	s_add_i32 s6, s10, s6
	s_cmpk_gt_i32 s6, 0x3ff
	s_mov_b32 s23, s7
	v_pk_mul_f32 v[6:7], v[92:93], v[4:5] op_sel_hi:[1,0]
	v_pk_mul_f32 v[4:5], v[94:95], v[4:5] op_sel_hi:[1,0]
	v_cvt_pk_bf16_f32 v222, v6, v7
	v_cvt_pk_bf16_f32 v223, v4, v5
	s_nop 1
	v_permlane32_swap_b32_e32 v220, v222
	v_permlane32_swap_b32_e32 v221, v223
	global_store_dwordx4 v[2:3], v[220:223], off offset:1120
	s_cbranch_scc1 .LBB0_865

; #define GAS __attribute__((address_space(1)))
; __device__ __forceinline__ void store_frag_bf16(bf16_t* base, const f32x16& a, float sc, int hi) {
; #pragma unroll
;   for (int g = 0; g < 4; ++g) {
;     u32x2 w; w.x = pk_bf16(a[4 * g] * sc, a[4 * g + 1] * sc); w.y = pk_bf16(a[4 * g + 2] * sc, a[4 * g + 3] * sc);
;     *(GAS u32x2*)(base + 8 * g + 4 * hi) = w;
;   }
; }
; template <int MODE>
; __device__ __forceinline__ void attn_unit(const Params& P, int b, int h, int qb, unsigned char* smem) {
;     ...
;   const float lt = l_run + __shfl_xor(l_run, 32);
;   const float inv = 1.0f / lt;
; #pragma unroll
;   for (int db = 0; db < 2; ++db) store_frag_bf16(O + (size_t)qi * 1024 + 32 * db, oacc[db], inv, hi);
; __device__ __forceinline__ void phase_attn_even(const Params& P, unsigned char* smem) {
;     ...
;   for (int u = bid; u < 1024; u += G) {
.LBB0_867:
	v_and_b32_e32 v2, 64, v147
	v_xor_b32_e32 v0, 32, v147
	v_add_u32_e32 v2, 64, v2
	v_cmp_lt_i32_e32 vcc, v0, v2
	s_lshl_b32 s7, s23, 12
	s_lshl_b32 s6, s22, 6
	v_cndmask_b32_e32 v0, v147, v0, vcc
	v_lshlrev_b32_e32 v0, 2, v0
	ds_bpermute_b32 v0, v0, v176
	s_lshl_b32 s10, s7, 11
	v_lshl_add_u64 v[2:3], v[104:105], 0, s[10:11]
	s_lshl_b32 s10, s6, 1
	v_lshl_add_u64 v[2:3], v[2:3], 0, s[10:11]
	s_waitcnt lgkmcnt(0)
	v_add_f32_e32 v0, v176, v0
	v_div_scale_f32 v4, s[12:13], v0, v0, 1.0
	v_rcp_f32_e32 v5, v4
	s_add_i32 s21, s21, s38
	s_cmpk_lt_i32 s21, 0x400
	v_fma_f32 v6, -v4, v5, 1.0
	v_fmac_f32_e32 v5, v6, v5
	v_div_scale_f32 v6, vcc, 1.0, v0, 1.0
	v_mul_f32_e32 v7, v6, v5
	v_fma_f32 v8, -v4, v7, v6
	v_fmac_f32_e32 v7, v8, v5
	v_fma_f32 v4, -v4, v7, v6
	v_div_fmas_f32 v4, v4, v5, v7
	v_div_fixup_f32 v4, v4, v0, 1.0
	v_lshlrev_b64 v[6:7], 11, v[106:107]
	v_lshl_add_u64 v[2:3], v[2:3], 0, v[6:7]
	v_lshlrev_b32_e32 v0, 3, v175
	v_lshl_add_u64 v[2:3], v[2:3], 0, v[0:1]
	v_mbcnt_lo_u32_b32 v224, -1, 0
	v_mbcnt_hi_u32_b32 v224, -1, v224
	v_and_b32_e32 v224, 32, v224
	v_lshrrev_b32_e32 v224, 2, v224
	v_mov_b32_e32 v225, 0
	v_lshl_add_u64 v[2:3], v[2:3], 0, v[224:225]
	v_pk_mul_f32 v[6:7], v[32:33], v[4:5] op_sel_hi:[1,0]
	v_pk_mul_f32 v[8:9], v[34:35], v[4:5] op_sel_hi:[1,0]
	v_cvt_pk_bf16_f32 v216, v6, v7
	v_cvt_pk_bf16_f32 v217, v8, v9
	v_pk_mul_f32 v[6:7], v[36:37], v[4:5] op_sel_hi:[1,0]
	v_pk_mul_f32 v[8:9], v[38:39], v[4:5] op_sel_hi:[1,0]
	v_cvt_pk_bf16_f32 v218, v6, v7
	v_cvt_pk_bf16_f32 v219, v8, v9
	s_nop 1
	v_permlane32_swap_b32_e32 v216, v218
	v_permlane32_swap_b32_e32 v217, v219
	global_store_dwordx4 v[2:3], v[216:219], off
	v_pk_mul_f32 v[6:7], v[40:41], v[4:5] op_sel_hi:[1,0]
	v_pk_mul_f32 v[8:9], v[42:43], v[4:5] op_sel_hi:[1,0]
	v_cvt_pk_bf16_f32 v220, v6, v7
	v_cvt_pk_bf16_f32 v221, v8, v9
	v_pk_mul_f32 v[6:7], v[44:45], v[4:5] op_sel_hi:[1,0]
	v_pk_mul_f32 v[8:9], v[46:47], v[4:5] op_sel_hi:[1,0]
	v_cvt_pk_bf16_f32 v222, v6, v7
	v_cvt_pk_bf16_f32 v223, v8, v9
	s_nop 1
	v_permlane32_swap_b32_e32 v220, v222
	v_permlane32_swap_b32_e32 v221, v223
	global_store_dwordx4 v[2:3], v[220:223], off offset:32
	v_pk_mul_f32 v[6:7], v[16:17], v[4:5] op_sel_hi:[1,0]
	v_pk_mul_f32 v[8:9], v[18:19], v[4:5] op_sel_hi:[1,0]
	v_cvt_pk_bf16_f32 v216, v6, v7
	v_cvt_pk_bf16_f32 v217, v8, v9
	v_pk_mul_f32 v[6:7], v[20:21], v[4:5] op_sel_hi:[1,0]
	v_pk_mul_f32 v[8:9], v[22:23], v[4:5] op_sel_hi:[1,0]
	v_cvt_pk_bf16_f32 v218, v6, v7
	v_cvt_pk_bf16_f32 v219, v8, v9
	s_nop 1
	v_permlane32_swap_b32_e32 v216, v218
	v_permlane32_swap_b32_e32 v217, v219
	global_store_dwordx4 v[2:3], v[216:219], off offset:64
	v_pk_mul_f32 v[6:7], v[24:25], v[4:5] op_sel_hi:[1,0]
	v_pk_mul_f32 v[8:9], v[26:27], v[4:5] op_sel_hi:[1,0]
	v_cvt_pk_bf16_f32 v220, v6, v7
	v_cvt_pk_bf16_f32 v221, v8, v9
	v_pk_mul_f32 v[6:7], v[28:29], v[4:5] op_sel_hi:[1,0]
	v_pk_mul_f32 v[4:5], v[30:31], v[4:5] op_sel_hi:[1,0]
	v_cvt_pk_bf16_f32 v222, v6, v7
	v_cvt_pk_bf16_f32 v223, v4, v5
	s_nop 1
	v_permlane32_swap_b32_e32 v220, v222
	v_permlane32_swap_b32_e32 v221, v223
	global_store_dwordx4 v[2:3], v[220:223], off offset:96
	s_cbranch_scc0 .LBB0_880

; #define GAS __attribute__((address_space(1)))
; __device__ __forceinline__ void store_frag_bf16(bf16_t* base, const f32x16& a, float sc, int hi) {
; #pragma unroll
;   for (int g = 0; g < 4; ++g) {
;     u32x2 w; w.x = pk_bf16(a[4 * g] * sc, a[4 * g + 1] * sc); w.y = pk_bf16(a[4 * g + 2] * sc, a[4 * g + 3] * sc);
;     *(GAS u32x2*)(base + 8 * g + 4 * hi) = w;
;   }
; }
; template <int MODE>
; __device__ __forceinline__ void attn_unit(const Params& P, int b, int h, int qb, unsigned char* smem) {
;     ...
;   const float lt = l_run + __shfl_xor(l_run, 32);
;   const float inv = 1.0f / lt;
; #pragma unroll
;   for (int db = 0; db < 2; ++db) store_frag_bf16(O + (size_t)qi * 1024 + 32 * db, oacc[db], inv, hi);
; __device__ __forceinline__ void phase_attn_odd(const Params& P, unsigned char* smem) {
;     ...
;   for (int j = 0;; ++j) {
;     const int u = j * G + ((j & 1) ? (G - 1 - bid) : bid);
;     if (u >= 2048) break;
.LBB0_1609:
	s_or_b64 exec, exec, s[6:7]
	v_cmp_lt_i32_e32 vcc, v130, v132
	v_lshlrev_b32_e32 v114, 1, v121
	s_nop 0
	v_cndmask_b32_e32 v0, v131, v130, vcc
	v_lshlrev_b32_e32 v0, 2, v0
	ds_bpermute_b32 v0, v0, v32
	s_barrier
	s_waitcnt lgkmcnt(0)
	v_add_f32_e32 v0, v32, v0
	v_div_scale_f32 v1, s[6:7], v0, v0, 1.0
	v_rcp_f32_e32 v2, v1
	v_div_scale_f32 v3, vcc, 1.0, v0, 1.0
	s_add_i32 s6, s23, 1
	v_fma_f32 v4, -v1, v2, 1.0
	v_fmac_f32_e32 v2, v4, v2
	v_mul_f32_e32 v4, v3, v2
	v_fma_f32 v5, -v1, v4, v3
	v_fmac_f32_e32 v4, v5, v2
	v_fma_f32 v1, -v1, v4, v3
	v_div_fmas_f32 v1, v1, v2, v4
	v_div_fixup_f32 v0, v1, v0, 1.0
	v_lshl_add_u64 v[2:3], v[116:117], 0, v[114:115]
	v_mbcnt_lo_u32_b32 v224, -1, 0
	v_mbcnt_hi_u32_b32 v224, -1, v224
	v_and_b32_e32 v224, 32, v224
	v_lshrrev_b32_e32 v224, 2, v224
	v_mov_b32_e32 v225, 0
	v_lshl_add_u64 v[2:3], v[2:3], 0, v[224:225]
	v_pk_mul_f32 v[4:5], v[80:81], v[0:1] op_sel_hi:[1,0]
	v_pk_mul_f32 v[6:7], v[82:83], v[0:1] op_sel_hi:[1,0]
	v_cvt_pk_bf16_f32 v216, v4, v5
	v_cvt_pk_bf16_f32 v217, v6, v7
	v_pk_mul_f32 v[4:5], v[84:85], v[0:1] op_sel_hi:[1,0]
	v_pk_mul_f32 v[6:7], v[86:87], v[0:1] op_sel_hi:[1,0]
	v_cvt_pk_bf16_f32 v218, v4, v5
	v_cvt_pk_bf16_f32 v219, v6, v7
	s_nop 1
	v_permlane32_swap_b32_e32 v216, v218
	v_permlane32_swap_b32_e32 v217, v219
	global_store_dwordx4 v[2:3], v[216:219], off
	v_pk_mul_f32 v[4:5], v[88:89], v[0:1] op_sel_hi:[1,0]
	v_pk_mul_f32 v[6:7], v[90:91], v[0:1] op_sel_hi:[1,0]
	v_cvt_pk_bf16_f32 v220, v4, v5
	v_cvt_pk_bf16_f32 v221, v6, v7
	v_pk_mul_f32 v[4:5], v[92:93], v[0:1] op_sel_hi:[1,0]
	v_pk_mul_f32 v[6:7], v[94:95], v[0:1] op_sel_hi:[1,0]
	v_cvt_pk_bf16_f32 v222, v4, v5
	v_cvt_pk_bf16_f32 v223, v6, v7
	s_nop 1
	v_permlane32_swap_b32_e32 v220, v222
	v_permlane32_swap_b32_e32 v221, v223
	global_store_dwordx4 v[2:3], v[220:223], off offset:32
	v_pk_mul_f32 v[4:5], v[64:65], v[0:1] op_sel_hi:[1,0]
	v_pk_mul_f32 v[6:7], v[66:67], v[0:1] op_sel_hi:[1,0]
	v_cvt_pk_bf16_f32 v216, v4, v5
	v_cvt_pk_bf16_f32 v217, v6, v7
	v_pk_mul_f32 v[4:5], v[68:69], v[0:1] op_sel_hi:[1,0]
	v_pk_mul_f32 v[6:7], v[70:71], v[0:1] op_sel_hi:[1,0]
	v_cvt_pk_bf16_f32 v218, v4, v5
	v_cvt_pk_bf16_f32 v219, v6, v7
	s_nop 1
	v_permlane32_swap_b32_e32 v216, v218
	v_permlane32_swap_b32_e32 v217, v219
	global_store_dwordx4 v[2:3], v[216:219], off offset:64
	s_bitcmp0_b32 s23, 0
	s_mul_i32 s7, s6, s38
	s_cselect_b32 s8, s53, s2
	v_pk_mul_f32 v[4:5], v[72:73], v[0:1] op_sel_hi:[1,0]
	v_pk_mul_f32 v[6:7], v[74:75], v[0:1] op_sel_hi:[1,0]
	v_cvt_pk_bf16_f32 v220, v4, v5
	v_cvt_pk_bf16_f32 v221, v6, v7
	s_add_i32 s24, s8, s7
	s_cmpk_gt_i32 s24, 0x7ff
	s_mov_b32 s23, s6
	v_pk_mul_f32 v[4:5], v[76:77], v[0:1] op_sel_hi:[1,0]
	v_pk_mul_f32 v[0:1], v[78:79], v[0:1] op_sel_hi:[1,0]
	v_cvt_pk_bf16_f32 v222, v4, v5
	v_cvt_pk_bf16_f32 v223, v0, v1
	s_nop 1
	v_permlane32_swap_b32_e32 v220, v222
	v_permlane32_swap_b32_e32 v221, v223
	global_store_dwordx4 v[2:3], v[220:223], off offset:96
	s_cbranch_scc1 .LBB0_1635
